# speedup vs baseline: 1.0046x; 1.0030x over previous
; DI int get_tid_(int wv) { int z = 0; asm volatile("" : "+v"(z)); asm volatile("" : "+s"(wv)); const int lane = __builtin_amdgcn_mbcnt_hi(~0u, __builtin_amdgcn_mbcnt_lo(~0u, z)); return (wv << 6) | lane; }
; DI unsigned xb_add(unsigned* p, unsigned v) { return __hip_atomic_fetch_add(p, v, __ATOMIC_RELAXED, __HIP_MEMORY_SCOPE_AGENT); }
; DI void xcd_barrier(const XcdBarrier& b, int wv) {
;     const int tid = get_tid_(wv);
;     asm volatile("s_waitcnt vmcnt(0)" ::: "memory");
;     __syncthreads();
;     if (tid == 0) {
;         unsigned* bar = b.bar;
;         __builtin_amdgcn_s_waitcnt(0);
;         unsigned nloc = b.st[0], nx = b.st[1];
;         if (nloc == 0u) { xcd_barrier_complete(bar, b.x, nloc, nx); b.st[0] = nloc; b.st[1] = nx; }
;         const unsigned old = xb_add(&bar[XB_XSUB(b.x)], 1u);
;         const unsigned gen = old / nloc;
;         if (old + 1u == (gen + 1u) * nloc) {
; __global__ void __launch_bounds__(NTHR) k_main(Params p_, int e_begin, int e_end) {
;     ...
;         if (e + 1 < e_end) { if (e == e_begin) cg::this_grid().sync(); else xcd_barrier(xb, p.wv); }
.LBB0_802:
	s_cmp_eq_u32 s17, 19
	s_cbranch_scc1 .Lfa_skipbar
	v_readlane_b32 s0, v253, 1
	v_readlane_b32 s1, v253, 2
	s_cmp_lg_u32 s17, -1
	s_mov_b64 s[0:1], -1
	s_cbranch_scc0 .LBB0_856
	v_mov_b32_e32 v0, v1
	s_mov_b32 s0, s64
	v_mbcnt_lo_u32_b32 v0, -1, v0
	v_mbcnt_hi_u32_b32 v0, -1, v0
	s_waitcnt vmcnt(0)
	v_lshl_or_b32 v0, s0, 6, v0
	v_cmp_eq_u32_e32 vcc, 0, v0
	s_waitcnt vmcnt(63) expcnt(7) lgkmcnt(15)
	s_barrier
	s_and_saveexec_b64 s[0:1], vcc
	s_cbranch_execz .LBB0_855
	s_add_i32 s8, 0, 0x20000
	v_mov_b32_e32 v0, s8
	s_waitcnt vmcnt(0) expcnt(0) lgkmcnt(0)
	ds_read_b32 v3, v0
	v_readlane_b32 s2, v254, 15
	s_waitcnt lgkmcnt(0)
	v_cmp_ne_u32_e32 vcc, 0, v3
	v_mov_b32_e32 v0, s2
	ds_read_b32 v2, v0
	s_cbranch_vccnz .LBB0_819
	s_load_dwordx2 s[2:3], s[24:25], 0x0
	s_load_dword s4, s[24:25], 0x8
	s_mov_b32 s10, 1
	s_waitcnt lgkmcnt(0)
	s_mul_i32 s9, s3, s2
	s_mul_i32 s9, s9, s4
	s_branch .LBB0_807

; DI void xcd_barrier(const XcdBarrier& b, int wv) {
;     ...
;     }
;     __syncthreads();
; }
; __global__ void __launch_bounds__(NTHR) k_main(Params p_, int e_begin, int e_end) {
;     ...
;         if (e + 1 < e_end) { if (e == e_begin) cg::this_grid().sync(); else xcd_barrier(xb, p.wv); }
.LBB0_855:
	s_or_b64 exec, exec, s[0:1]
	s_mov_b64 s[0:1], 0
	s_waitcnt lgkmcnt(0)
	s_barrier
	s_branch .LBB0_856
.Lfa_skipbar:
	s_mov_b64 s[0:1], 0
.LBB0_856:
	s_and_b64 vcc, exec, s[0:1]
	s_cbranch_vccnz .LBB0_857
	s_getpc_b64 s[98:99]
